# GEMM K-loop: DMA completion wait (vmcnt) moved from before the first barrier to before the second barrier of each superphase (more latency tolerance, same data dependences)
# baseline (speedup 1.0000x reference)
.LBB0_191:
	s_add_i32 s10, s8, 2
	s_add_u32 s11, s58, s2
	s_addc_u32 s9, s59, s3
	s_add_u32 s12, s42, s2
	s_addc_u32 s13, s43, s3
	s_add_i32 s24, 0, 0x10000
	s_cmp_eq_u32 s28, s8
	s_cselect_b32 s9, s73, s9
	s_cselect_b32 s8, s72, s11
	s_cselect_b32 s13, s57, s13
	s_cselect_b32 s12, s56, s12
	s_add_i32 s11, 0, 0x14000
	v_add_u32_e32 v144, s24, v252
	v_add_u32_e32 v160, s11, v252
	ds_read_b128 v[132:135], v144
	ds_read_b128 v[136:139], v144 offset:1024
	ds_read_b128 v[140:143], v144 offset:2048
	ds_read_b128 v[144:147], v144 offset:3072
	ds_read_b128 v[148:151], v160
	ds_read_b128 v[152:155], v160 offset:1024
	ds_read_b128 v[156:159], v160 offset:2048
	ds_read_b128 v[160:163], v160 offset:3072
	v_lshl_add_u64 v[196:197], s[58:59], 0, v[130:131]
	s_add_i32 m0, s69, 0xc000
	ds_read_b128 v[164:167], v249
	ds_read_b128 v[168:171], v249 offset:1024
	ds_read_b128 v[172:175], v249 offset:2048
	ds_read_b128 v[176:179], v249 offset:3072
	ds_read_b128 v[180:183], v249 offset:4096
	ds_read_b128 v[184:187], v249 offset:5120
	ds_read_b128 v[188:191], v249 offset:6144
	ds_read_b128 v[192:195], v249 offset:7168
	global_load_lds_dwordx4 v[196:197], off
	v_lshl_add_u64 v[196:197], s[58:59], 0, v[128:129]
	s_add_i32 m0, s69, 0xe000
	s_nop 0
	global_load_lds_dwordx4 v[196:197], off
	s_waitcnt lgkmcnt(0)
	s_barrier
	s_setprio 1
	s_waitcnt lgkmcnt(0)
	v_mfma_f32_16x16x32_bf16 v[124:127], v[132:135], v[164:167], v[124:127]
	v_mfma_f32_16x16x32_bf16 v[120:123], v[140:143], v[164:167], v[120:123]
	v_mfma_f32_16x16x32_bf16 v[116:119], v[132:135], v[172:175], v[116:119]
	v_mfma_f32_16x16x32_bf16 v[112:115], v[140:143], v[172:175], v[112:115]
	v_mfma_f32_16x16x32_bf16 v[108:111], v[132:135], v[180:183], v[108:111]
	v_mfma_f32_16x16x32_bf16 v[100:103], v[140:143], v[180:183], v[100:103]
	v_mfma_f32_16x16x32_bf16 v[92:95], v[132:135], v[188:191], v[92:95]
	v_mfma_f32_16x16x32_bf16 v[84:87], v[140:143], v[188:191], v[84:87]
	v_mfma_f32_16x16x32_bf16 v[124:127], v[136:139], v[168:171], v[124:127]
	v_mfma_f32_16x16x32_bf16 v[120:123], v[144:147], v[168:171], v[120:123]
	v_mfma_f32_16x16x32_bf16 v[116:119], v[136:139], v[176:179], v[116:119]
	v_mfma_f32_16x16x32_bf16 v[112:115], v[144:147], v[176:179], v[112:115]
	v_mfma_f32_16x16x32_bf16 v[108:111], v[136:139], v[184:187], v[108:111]
	v_mfma_f32_16x16x32_bf16 v[100:103], v[144:147], v[184:187], v[100:103]
	v_mfma_f32_16x16x32_bf16 v[92:95], v[136:139], v[192:195], v[92:95]
	v_mfma_f32_16x16x32_bf16 v[84:87], v[144:147], v[192:195], v[84:87]
	s_setprio 0
	s_setprio 1
	v_mfma_f32_16x16x32_bf16 v[104:107], v[148:151], v[164:167], v[104:107]
	v_mfma_f32_16x16x32_bf16 v[96:99], v[156:159], v[164:167], v[96:99]
	v_mfma_f32_16x16x32_bf16 v[88:91], v[148:151], v[172:175], v[88:91]
	v_mfma_f32_16x16x32_bf16 v[80:83], v[156:159], v[172:175], v[80:83]
	v_mfma_f32_16x16x32_bf16 v[76:79], v[148:151], v[180:183], v[76:79]
	v_mfma_f32_16x16x32_bf16 v[72:75], v[156:159], v[180:183], v[72:75]
	v_mfma_f32_16x16x32_bf16 v[68:71], v[148:151], v[188:191], v[68:71]
	v_mfma_f32_16x16x32_bf16 v[64:67], v[156:159], v[188:191], v[64:67]
	v_mfma_f32_16x16x32_bf16 v[104:107], v[152:155], v[168:171], v[104:107]
	v_mfma_f32_16x16x32_bf16 v[96:99], v[160:163], v[168:171], v[96:99]
	v_mfma_f32_16x16x32_bf16 v[88:91], v[152:155], v[176:179], v[88:91]
	v_mfma_f32_16x16x32_bf16 v[80:83], v[160:163], v[176:179], v[80:83]
	v_mfma_f32_16x16x32_bf16 v[76:79], v[152:155], v[184:187], v[76:79]
	v_mfma_f32_16x16x32_bf16 v[72:75], v[160:163], v[184:187], v[72:75]
	v_mfma_f32_16x16x32_bf16 v[68:71], v[152:155], v[192:195], v[68:71]
	v_mfma_f32_16x16x32_bf16 v[64:67], v[160:163], v[192:195], v[64:67]
	s_waitcnt vmcnt(8)
	s_setprio 0
	s_barrier
	s_add_i32 s24, s24, s89
	v_lshl_add_u64 v[196:197], s[12:13], 0, v[212:213]
	s_mov_b32 m0, s24
	ds_read_b128 v[164:167], v249 offset:16384
	ds_read_b128 v[168:171], v249 offset:17408
	ds_read_b128 v[172:175], v249 offset:18432
	ds_read_b128 v[176:179], v249 offset:19456
	ds_read_b128 v[180:183], v249 offset:20480
	ds_read_b128 v[184:187], v249 offset:21504
	ds_read_b128 v[188:191], v249 offset:22528
	ds_read_b128 v[192:195], v249 offset:23552
	global_load_lds_dwordx4 v[196:197], off
	s_add_i32 m0, s24, 0x2000
	v_lshl_add_u64 v[198:199], s[12:13], 0, v[216:217]
	s_add_u32 s12, s12, s52
	s_addc_u32 s13, s13, s53
	s_add_i32 s11, s11, s89
	global_load_lds_dwordx4 v[198:199], off
	v_lshl_add_u64 v[200:201], s[12:13], 0, v[212:213]
	s_mov_b32 m0, s11
	v_lshl_add_u64 v[202:203], s[12:13], 0, v[216:217]
	global_load_lds_dwordx4 v[200:201], off
	s_add_i32 m0, s11, 0x2000
	v_lshl_add_u64 v[204:205], s[8:9], 0, v[210:211]
	global_load_lds_dwordx4 v[202:203], off
	s_mov_b32 m0, s69
	v_lshl_add_u64 v[206:207], s[8:9], 0, v[214:215]
	global_load_lds_dwordx4 v[204:205], off
	s_mov_b32 m0, s25
	s_nop 0
	global_load_lds_dwordx4 v[206:207], off
	s_waitcnt lgkmcnt(0)
	s_barrier
	s_setprio 1
	s_waitcnt lgkmcnt(0)
	v_mfma_f32_16x16x32_bf16 v[60:63], v[132:135], v[164:167], v[60:63]
	v_mfma_f32_16x16x32_bf16 v[56:59], v[140:143], v[164:167], v[56:59]
	v_mfma_f32_16x16x32_bf16 v[52:55], v[132:135], v[172:175], v[52:55]
	v_mfma_f32_16x16x32_bf16 v[48:51], v[140:143], v[172:175], v[48:51]
	v_mfma_f32_16x16x32_bf16 v[44:47], v[132:135], v[180:183], v[44:47]
	v_mfma_f32_16x16x32_bf16 v[36:39], v[140:143], v[180:183], v[36:39]
	v_mfma_f32_16x16x32_bf16 v[28:31], v[132:135], v[188:191], v[28:31]
	v_mfma_f32_16x16x32_bf16 v[20:23], v[140:143], v[188:191], v[20:23]
	v_mfma_f32_16x16x32_bf16 v[60:63], v[136:139], v[168:171], v[60:63]
	v_mfma_f32_16x16x32_bf16 v[56:59], v[144:147], v[168:171], v[56:59]
	v_mfma_f32_16x16x32_bf16 v[52:55], v[136:139], v[176:179], v[52:55]
	v_mfma_f32_16x16x32_bf16 v[48:51], v[144:147], v[176:179], v[48:51]
	v_mfma_f32_16x16x32_bf16 v[44:47], v[136:139], v[184:187], v[44:47]
	v_mfma_f32_16x16x32_bf16 v[36:39], v[144:147], v[184:187], v[36:39]
	v_mfma_f32_16x16x32_bf16 v[28:31], v[136:139], v[192:195], v[28:31]
	v_mfma_f32_16x16x32_bf16 v[20:23], v[144:147], v[192:195], v[20:23]
	s_setprio 0
	s_setprio 1
	v_mfma_f32_16x16x32_bf16 v[40:43], v[148:151], v[164:167], v[40:43]
	v_mfma_f32_16x16x32_bf16 v[32:35], v[156:159], v[164:167], v[32:35]
	v_mfma_f32_16x16x32_bf16 v[24:27], v[148:151], v[172:175], v[24:27]
	v_mfma_f32_16x16x32_bf16 v[16:19], v[156:159], v[172:175], v[16:19]
	v_mfma_f32_16x16x32_bf16 v[12:15], v[148:151], v[180:183], v[12:15]
	v_mfma_f32_16x16x32_bf16 v[8:11], v[156:159], v[180:183], v[8:11]
	v_mfma_f32_16x16x32_bf16 v[4:7], v[148:151], v[188:191], v[4:7]
	v_mfma_f32_16x16x32_bf16 v[0:3], v[156:159], v[188:191], v[0:3]
	v_mfma_f32_16x16x32_bf16 v[40:43], v[152:155], v[168:171], v[40:43]
	v_mfma_f32_16x16x32_bf16 v[32:35], v[160:163], v[168:171], v[32:35]
	v_mfma_f32_16x16x32_bf16 v[24:27], v[152:155], v[176:179], v[24:27]
	v_mfma_f32_16x16x32_bf16 v[16:19], v[160:163], v[176:179], v[16:19]
	v_mfma_f32_16x16x32_bf16 v[12:15], v[152:155], v[184:187], v[12:15]
	v_mfma_f32_16x16x32_bf16 v[8:11], v[160:163], v[184:187], v[8:11]
	v_mfma_f32_16x16x32_bf16 v[4:7], v[152:155], v[192:195], v[4:7]
	v_mfma_f32_16x16x32_bf16 v[0:3], v[160:163], v[192:195], v[0:3]
	s_waitcnt vmcnt(8)
	s_setprio 0
	s_barrier
	s_add_i32 s11, 0, 0x18000
	s_add_i32 s12, 0, 0x1c000
	v_add_u32_e32 v144, s11, v252
	v_add_u32_e32 v160, s12, v252
	ds_read_b128 v[132:135], v144
	ds_read_b128 v[136:139], v144 offset:1024
	ds_read_b128 v[140:143], v144 offset:2048
	ds_read_b128 v[144:147], v144 offset:3072
	ds_read_b128 v[148:151], v160
	ds_read_b128 v[152:155], v160 offset:1024
	ds_read_b128 v[156:159], v160 offset:2048
	ds_read_b128 v[160:163], v160 offset:3072
	s_add_u32 s8, s8, 0x80000
	s_addc_u32 s9, s9, 0
	s_mov_b32 m0, s83
	v_lshl_add_u64 v[224:225], s[8:9], 0, v[210:211]
	ds_read_b128 v[164:167], v249 offset:32768
	ds_read_b128 v[168:171], v249 offset:33792
	ds_read_b128 v[172:175], v249 offset:34816
	ds_read_b128 v[176:179], v249 offset:35840
	ds_read_b128 v[180:183], v249 offset:36864
	ds_read_b128 v[184:187], v249 offset:37888
	ds_read_b128 v[188:191], v249 offset:38912
	ds_read_b128 v[192:195], v249 offset:39936
	global_load_lds_dwordx4 v[224:225], off
	v_lshl_add_u64 v[224:225], s[8:9], 0, v[214:215]
	s_mov_b32 m0, s30
	s_nop 0
	global_load_lds_dwordx4 v[224:225], off
	s_waitcnt lgkmcnt(0)
	s_barrier
	s_setprio 1
	s_waitcnt lgkmcnt(0)
	v_mfma_f32_16x16x32_bf16 v[124:127], v[132:135], v[164:167], v[124:127]
	v_mfma_f32_16x16x32_bf16 v[120:123], v[140:143], v[164:167], v[120:123]
	v_mfma_f32_16x16x32_bf16 v[116:119], v[132:135], v[172:175], v[116:119]
	v_mfma_f32_16x16x32_bf16 v[112:115], v[140:143], v[172:175], v[112:115]
	v_mfma_f32_16x16x32_bf16 v[108:111], v[132:135], v[180:183], v[108:111]
	v_mfma_f32_16x16x32_bf16 v[100:103], v[140:143], v[180:183], v[100:103]
	v_mfma_f32_16x16x32_bf16 v[92:95], v[132:135], v[188:191], v[92:95]
	v_mfma_f32_16x16x32_bf16 v[84:87], v[140:143], v[188:191], v[84:87]
	v_mfma_f32_16x16x32_bf16 v[124:127], v[136:139], v[168:171], v[124:127]
	v_mfma_f32_16x16x32_bf16 v[120:123], v[144:147], v[168:171], v[120:123]
	v_mfma_f32_16x16x32_bf16 v[116:119], v[136:139], v[176:179], v[116:119]
	v_mfma_f32_16x16x32_bf16 v[112:115], v[144:147], v[176:179], v[112:115]
	v_mfma_f32_16x16x32_bf16 v[108:111], v[136:139], v[184:187], v[108:111]
	v_mfma_f32_16x16x32_bf16 v[100:103], v[144:147], v[184:187], v[100:103]
	v_mfma_f32_16x16x32_bf16 v[92:95], v[136:139], v[192:195], v[92:95]
	v_mfma_f32_16x16x32_bf16 v[84:87], v[144:147], v[192:195], v[84:87]
	s_setprio 0
	s_setprio 1
	v_mfma_f32_16x16x32_bf16 v[104:107], v[148:151], v[164:167], v[104:107]
	v_mfma_f32_16x16x32_bf16 v[96:99], v[156:159], v[164:167], v[96:99]
	v_mfma_f32_16x16x32_bf16 v[88:91], v[148:151], v[172:175], v[88:91]
	v_mfma_f32_16x16x32_bf16 v[80:83], v[156:159], v[172:175], v[80:83]
	v_mfma_f32_16x16x32_bf16 v[76:79], v[148:151], v[180:183], v[76:79]
	v_mfma_f32_16x16x32_bf16 v[72:75], v[156:159], v[180:183], v[72:75]
	v_mfma_f32_16x16x32_bf16 v[68:71], v[148:151], v[188:191], v[68:71]
	v_mfma_f32_16x16x32_bf16 v[64:67], v[156:159], v[188:191], v[64:67]
	v_mfma_f32_16x16x32_bf16 v[104:107], v[152:155], v[168:171], v[104:107]
	v_mfma_f32_16x16x32_bf16 v[96:99], v[160:163], v[168:171], v[96:99]
	v_mfma_f32_16x16x32_bf16 v[88:91], v[152:155], v[176:179], v[88:91]
	v_mfma_f32_16x16x32_bf16 v[80:83], v[160:163], v[176:179], v[80:83]
	v_mfma_f32_16x16x32_bf16 v[76:79], v[152:155], v[184:187], v[76:79]
	v_mfma_f32_16x16x32_bf16 v[72:75], v[160:163], v[184:187], v[72:75]
	v_mfma_f32_16x16x32_bf16 v[68:71], v[152:155], v[192:195], v[68:71]
	v_mfma_f32_16x16x32_bf16 v[64:67], v[160:163], v[192:195], v[64:67]
	s_waitcnt vmcnt(8)
	s_setprio 0
	s_barrier
	s_add_i32 s8, s11, s89
	v_lshl_add_u64 v[196:197], v[196:197], 0, s[96:97]
	s_mov_b32 m0, s8
	ds_read_b128 v[164:167], v249 offset:49152
	ds_read_b128 v[168:171], v249 offset:50176
	ds_read_b128 v[172:175], v249 offset:51200
	ds_read_b128 v[176:179], v249 offset:52224
	ds_read_b128 v[180:183], v249 offset:53248
	ds_read_b128 v[184:187], v249 offset:54272
	ds_read_b128 v[188:191], v249 offset:55296
	ds_read_b128 v[192:195], v249 offset:56320
	global_load_lds_dwordx4 v[196:197], off
	v_lshl_add_u64 v[196:197], v[198:199], 0, s[96:97]
	s_add_i32 m0, s8, 0x2000
	s_add_i32 s8, s12, s89
	global_load_lds_dwordx4 v[196:197], off
	v_lshl_add_u64 v[196:197], v[200:201], 0, s[96:97]
	s_mov_b32 m0, s8
	s_nop 0
	global_load_lds_dwordx4 v[196:197], off
	v_lshl_add_u64 v[196:197], v[202:203], 0, s[96:97]
	s_add_i32 m0, s8, 0x2000
	s_nop 0
	global_load_lds_dwordx4 v[196:197], off
	v_lshl_add_u64 v[196:197], v[204:205], 0, s[96:97]
	s_mov_b32 m0, s36
	s_nop 0
	global_load_lds_dwordx4 v[196:197], off
	v_lshl_add_u64 v[196:197], v[206:207], 0, s[96:97]
	s_mov_b32 m0, s37
	s_nop 0
	global_load_lds_dwordx4 v[196:197], off
	s_waitcnt lgkmcnt(0)
	s_barrier
	s_setprio 1
	s_waitcnt lgkmcnt(0)
	v_mfma_f32_16x16x32_bf16 v[60:63], v[132:135], v[164:167], v[60:63]
	v_mfma_f32_16x16x32_bf16 v[56:59], v[140:143], v[164:167], v[56:59]
	v_mfma_f32_16x16x32_bf16 v[52:55], v[132:135], v[172:175], v[52:55]
	v_mfma_f32_16x16x32_bf16 v[48:51], v[140:143], v[172:175], v[48:51]
	v_mfma_f32_16x16x32_bf16 v[44:47], v[132:135], v[180:183], v[44:47]
	v_mfma_f32_16x16x32_bf16 v[36:39], v[140:143], v[180:183], v[36:39]
	v_mfma_f32_16x16x32_bf16 v[28:31], v[132:135], v[188:191], v[28:31]
	v_mfma_f32_16x16x32_bf16 v[20:23], v[140:143], v[188:191], v[20:23]
	v_mfma_f32_16x16x32_bf16 v[60:63], v[136:139], v[168:171], v[60:63]
	v_mfma_f32_16x16x32_bf16 v[56:59], v[144:147], v[168:171], v[56:59]
	v_mfma_f32_16x16x32_bf16 v[52:55], v[136:139], v[176:179], v[52:55]
	v_mfma_f32_16x16x32_bf16 v[48:51], v[144:147], v[176:179], v[48:51]
	v_mfma_f32_16x16x32_bf16 v[44:47], v[136:139], v[184:187], v[44:47]
	v_mfma_f32_16x16x32_bf16 v[36:39], v[144:147], v[184:187], v[36:39]
	v_mfma_f32_16x16x32_bf16 v[28:31], v[136:139], v[192:195], v[28:31]
	v_mfma_f32_16x16x32_bf16 v[20:23], v[144:147], v[192:195], v[20:23]
	s_setprio 0
	s_setprio 1
	v_mfma_f32_16x16x32_bf16 v[40:43], v[148:151], v[164:167], v[40:43]
	v_mfma_f32_16x16x32_bf16 v[32:35], v[156:159], v[164:167], v[32:35]
	v_mfma_f32_16x16x32_bf16 v[24:27], v[148:151], v[172:175], v[24:27]
	v_mfma_f32_16x16x32_bf16 v[16:19], v[156:159], v[172:175], v[16:19]
	v_mfma_f32_16x16x32_bf16 v[12:15], v[148:151], v[180:183], v[12:15]
	v_mfma_f32_16x16x32_bf16 v[8:11], v[156:159], v[180:183], v[8:11]
	v_mfma_f32_16x16x32_bf16 v[4:7], v[148:151], v[188:191], v[4:7]
	v_mfma_f32_16x16x32_bf16 v[0:3], v[156:159], v[188:191], v[0:3]
	v_mfma_f32_16x16x32_bf16 v[40:43], v[152:155], v[168:171], v[40:43]
	v_mfma_f32_16x16x32_bf16 v[32:35], v[160:163], v[168:171], v[32:35]
	v_mfma_f32_16x16x32_bf16 v[24:27], v[152:155], v[176:179], v[24:27]
	v_mfma_f32_16x16x32_bf16 v[16:19], v[160:163], v[176:179], v[16:19]
	v_mfma_f32_16x16x32_bf16 v[12:15], v[152:155], v[184:187], v[12:15]
	v_mfma_f32_16x16x32_bf16 v[8:11], v[160:163], v[184:187], v[8:11]
	v_mfma_f32_16x16x32_bf16 v[4:7], v[152:155], v[192:195], v[4:7]
	v_mfma_f32_16x16x32_bf16 v[0:3], v[160:163], v[192:195], v[0:3]
	s_waitcnt vmcnt(8)
	s_setprio 0
	s_barrier
	s_add_u32 s2, s2, 0x100
	s_addc_u32 s3, s3, 0
	v_lshl_add_u64 v[130:131], v[130:131], 0, s[74:75]
	v_lshl_add_u64 v[128:129], v[128:129], 0, s[74:75]
	s_cmp_ge_u32 s10, s86
	s_mov_b32 s8, s10
	s_cbranch_scc0 .LBB0_191
	s_and_b64 vcc, exec, s[66:67]
	s_cbranch_vccz .LBB0_214
	s_barrier
	s_andn2_b64 vcc, exec, s[38:39]
	s_cbranch_vccnz .LBB0_215
